# residual epilogues of the FFN-0 down and attention output-projection GEMMs also batched: 32 bf16 residual loads issued ahead, counted waits
# speedup vs baseline: 1.0071x; 1.0005x over previous
.LBB0_1548:
	v_lshl_add_u32 v142, s62, 8, v144
	v_lshl_add_u32 v140, s63, 8, v146
	v_ashrrev_i32_e32 v143, 31, v142
	v_ashrrev_i32_e32 v141, 31, v140
	v_lshlrev_b64 v[152:153], 10, v[142:143]
	v_lshl_add_u64 v[152:153], v[152:153], 0, v[140:141]
	v_lshlrev_b64 v[152:153], 1, v[152:153]
	v_lshl_add_u64 v[154:155], s[28:29], 0, v[152:153]
	v_add_u32_e32 v252, 0x0, v142
	v_ashrrev_i32_e32 v253, 31, v252
	v_lshlrev_b64 v[252:253], 10, v[252:253]
	v_lshl_add_u64 v[252:253], v[252:253], 0, v[140:141]
	v_lshl_add_u64 v[252:253], v[252:253], 1, s[28:29]
	global_load_dwordx2 v[172:173], v[252:253], off
	global_load_dwordx2 v[174:175], v[252:253], off offset:32
	global_load_dwordx2 v[176:177], v[252:253], off offset:256
	global_load_dwordx2 v[178:179], v[252:253], off offset:288
	v_add_u32_e32 v250, 0x10, v142
	v_ashrrev_i32_e32 v251, 31, v250
	v_lshlrev_b64 v[250:251], 10, v[250:251]
	v_lshl_add_u64 v[250:251], v[250:251], 0, v[140:141]
	v_lshl_add_u64 v[250:251], v[250:251], 1, s[28:29]
	global_load_dwordx2 v[184:185], v[250:251], off
	global_load_dwordx2 v[186:187], v[250:251], off offset:32
	global_load_dwordx2 v[188:189], v[250:251], off offset:256
	global_load_dwordx2 v[190:191], v[250:251], off offset:288
	v_add_u32_e32 v252, 0x20, v142
	v_ashrrev_i32_e32 v253, 31, v252
	v_lshlrev_b64 v[252:253], 10, v[252:253]
	v_lshl_add_u64 v[252:253], v[252:253], 0, v[140:141]
	v_lshl_add_u64 v[252:253], v[252:253], 1, s[28:29]
	global_load_dwordx2 v[192:193], v[252:253], off
	global_load_dwordx2 v[194:195], v[252:253], off offset:32
	global_load_dwordx2 v[196:197], v[252:253], off offset:256
	global_load_dwordx2 v[198:199], v[252:253], off offset:288
	v_add_u32_e32 v250, 0x30, v142
	v_ashrrev_i32_e32 v251, 31, v250
	v_lshlrev_b64 v[250:251], 10, v[250:251]
	v_lshl_add_u64 v[250:251], v[250:251], 0, v[140:141]
	v_lshl_add_u64 v[250:251], v[250:251], 1, s[28:29]
	global_load_dwordx2 v[200:201], v[250:251], off
	global_load_dwordx2 v[202:203], v[250:251], off offset:32
	global_load_dwordx2 v[204:205], v[250:251], off offset:256
	global_load_dwordx2 v[206:207], v[250:251], off offset:288
	v_add_u32_e32 v252, 0x80, v142
	v_ashrrev_i32_e32 v253, 31, v252
	v_lshlrev_b64 v[252:253], 10, v[252:253]
	v_lshl_add_u64 v[252:253], v[252:253], 0, v[140:141]
	v_lshl_add_u64 v[252:253], v[252:253], 1, s[28:29]
	global_load_dwordx2 v[208:209], v[252:253], off
	global_load_dwordx2 v[210:211], v[252:253], off offset:32
	global_load_dwordx2 v[222:223], v[252:253], off offset:256
	global_load_dwordx2 v[224:225], v[252:253], off offset:288
	v_add_u32_e32 v250, 0x90, v142
	v_ashrrev_i32_e32 v251, 31, v250
	v_lshlrev_b64 v[250:251], 10, v[250:251]
	v_lshl_add_u64 v[250:251], v[250:251], 0, v[140:141]
	v_lshl_add_u64 v[250:251], v[250:251], 1, s[28:29]
	global_load_dwordx2 v[226:227], v[250:251], off
	global_load_dwordx2 v[228:229], v[250:251], off offset:32
	global_load_dwordx2 v[230:231], v[250:251], off offset:256
	global_load_dwordx2 v[232:233], v[250:251], off offset:288
	v_add_u32_e32 v252, 0xa0, v142
	v_ashrrev_i32_e32 v253, 31, v252
	v_lshlrev_b64 v[252:253], 10, v[252:253]
	v_lshl_add_u64 v[252:253], v[252:253], 0, v[140:141]
	v_lshl_add_u64 v[252:253], v[252:253], 1, s[28:29]
	global_load_dwordx2 v[234:235], v[252:253], off
	global_load_dwordx2 v[236:237], v[252:253], off offset:32
	global_load_dwordx2 v[238:239], v[252:253], off offset:256
	global_load_dwordx2 v[240:241], v[252:253], off offset:288
	v_add_u32_e32 v250, 0xb0, v142
	v_ashrrev_i32_e32 v251, 31, v250
	v_lshlrev_b64 v[250:251], 10, v[250:251]
	v_lshl_add_u64 v[250:251], v[250:251], 0, v[140:141]
	v_lshl_add_u64 v[250:251], v[250:251], 1, s[28:29]
	global_load_dwordx2 v[242:243], v[250:251], off
	global_load_dwordx2 v[244:245], v[250:251], off offset:32
	global_load_dwordx2 v[246:247], v[250:251], off offset:256
	global_load_dwordx2 v[248:249], v[250:251], off offset:288
	s_nop 0
	v_and_b32_e32 v162, 64, v150
	v_xor_b32_e32 v151, 16, v150
	v_add_u32_e32 v162, 64, v162
	v_xor_b32_e32 v163, 32, v150
	v_cmp_lt_i32_e32 vcc, v151, v162
	v_lshl_add_u64 v[152:153], s[26:27], 0, v[152:153]
	s_waitcnt vmcnt(28)
	v_and_b32_e32 v165, 0xffff0000, v175
	v_cndmask_b32_e32 v151, v150, v151, vcc
	v_cmp_lt_i32_e32 vcc, v163, v162
	v_lshlrev_b32_e32 v162, 16, v173
	v_lshlrev_b32_e32 v164, 16, v175
	v_cndmask_b32_e32 v170, v150, v163, vcc
	v_and_b32_e32 v163, 0xffff0000, v173
	v_and_b32_e32 v157, 0xffff0000, v172
	v_lshlrev_b32_e32 v156, 16, v172
	v_and_b32_e32 v159, 0xffff0000, v174
	v_lshlrev_b32_e32 v158, 16, v174
	v_and_b32_e32 v167, 0xffff0000, v177
	v_lshlrev_b32_e32 v166, 16, v177
	v_and_b32_e32 v161, 0xffff0000, v176
	v_lshlrev_b32_e32 v160, 16, v176
	v_and_b32_e32 v169, 0xffff0000, v179
	v_lshlrev_b32_e32 v168, 16, v179
	v_and_b32_e32 v155, 0xffff0000, v178
	v_lshlrev_b32_e32 v154, 16, v178
	v_pk_add_f32 v[126:127], v[126:127], v[162:163]
	v_pk_add_f32 v[124:125], v[124:125], v[156:157]
	v_pk_add_f32 v[122:123], v[122:123], v[164:165]
	v_pk_add_f32 v[120:121], v[120:121], v[158:159]
	v_pk_add_f32 v[118:119], v[118:119], v[166:167]
	v_pk_add_f32 v[116:117], v[116:117], v[160:161]
	v_pk_add_f32 v[156:157], v[114:115], v[168:169]
	v_pk_add_f32 v[154:155], v[112:113], v[154:155]
	v_cvt_pk_bf16_f32 v112, v124, v125
	v_cvt_pk_bf16_f32 v113, v126, v127
	v_mul_f32_e32 v125, v125, v125
	v_mul_f32_e32 v127, v127, v127
	v_cvt_pk_bf16_f32 v114, v120, v121
	v_cvt_pk_bf16_f32 v115, v122, v123
	v_mul_f32_e32 v121, v121, v121
	v_mul_f32_e32 v123, v123, v123
	v_mul_f32_e32 v158, v117, v117
	v_mul_f32_e32 v159, v119, v119
	v_fmac_f32_e32 v125, v124, v124
	v_fmac_f32_e32 v127, v126, v126
	v_fmac_f32_e32 v121, v120, v120
	v_fmac_f32_e32 v123, v122, v122
	v_mul_f32_e32 v160, v155, v155
	v_mul_f32_e32 v161, v157, v157
	v_fmac_f32_e32 v158, v116, v116
	v_fmac_f32_e32 v159, v118, v118
	v_add_f32_e32 v120, v125, v127
	v_add_f32_e32 v121, v121, v123
	v_fmac_f32_e32 v160, v154, v154
	v_fmac_f32_e32 v161, v156, v156
	v_add_f32_e32 v122, v158, v159
	v_add_f32_e32 v120, v120, v121
	v_add_f32_e32 v123, v160, v161
	v_add_f32_e32 v120, v120, v122
	v_lshlrev_b32_e32 v151, 2, v151
	v_add_f32_e32 v120, v120, v123
	ds_bpermute_b32 v121, v151, v120
	global_store_dwordx2 v[152:153], v[112:113], off
	global_store_dwordx2 v[152:153], v[114:115], off offset:32
	v_lshlrev_b32_e32 v114, 2, v170
	v_cvt_pk_bf16_f32 v116, v116, v117
	v_cvt_pk_bf16_f32 v117, v118, v119
	s_waitcnt lgkmcnt(0)
	v_add_f32_e32 v112, v120, v121
	ds_bpermute_b32 v113, v114, v112
	global_store_dwordx2 v[152:153], v[116:117], off offset:256
	v_cvt_pk_bf16_f32 v116, v154, v155
	v_cvt_pk_bf16_f32 v117, v156, v157
	global_store_dwordx2 v[152:153], v[116:117], off offset:288
	s_and_saveexec_b64 s[34:35], s[2:3]
	s_cbranch_execz .LBB0_1550
	v_lshl_add_u64 v[116:117], v[142:143], 2, s[14:15]
	s_waitcnt lgkmcnt(0)
	v_add_f32_e32 v112, v112, v113
	global_atomic_add_f32 v[116:117], v112, off
.LBB0_1550:
	s_or_b64 exec, exec, s[34:35]
	v_or_b32_e32 v112, 16, v142
	s_waitcnt lgkmcnt(0)
	v_ashrrev_i32_e32 v113, 31, v112
	v_lshlrev_b64 v[116:117], 10, v[112:113]
	v_lshl_add_u64 v[116:117], v[116:117], 0, v[140:141]
	v_lshlrev_b64 v[116:117], 1, v[116:117]
	v_lshl_add_u64 v[118:119], s[28:29], 0, v[116:117]
	s_nop 0
	v_lshl_add_u64 v[116:117], s[26:27], 0, v[116:117]
	s_waitcnt vmcnt(31)
	v_and_b32_e32 v127, 0xffff0000, v185
	v_lshlrev_b32_e32 v126, 16, v185
	v_and_b32_e32 v121, 0xffff0000, v184
	v_lshlrev_b32_e32 v120, 16, v184
	s_waitcnt vmcnt(30)
	v_and_b32_e32 v153, 0xffff0000, v187
	v_lshlrev_b32_e32 v152, 16, v187
	v_and_b32_e32 v123, 0xffff0000, v186
	v_lshlrev_b32_e32 v122, 16, v186
	s_waitcnt vmcnt(29)
	v_and_b32_e32 v155, 0xffff0000, v189
	v_lshlrev_b32_e32 v154, 16, v189
	v_and_b32_e32 v125, 0xffff0000, v188
	v_lshlrev_b32_e32 v124, 16, v188
	s_waitcnt vmcnt(28)
	v_and_b32_e32 v157, 0xffff0000, v191
	v_lshlrev_b32_e32 v156, 16, v191
	v_and_b32_e32 v119, 0xffff0000, v190
	v_lshlrev_b32_e32 v118, 16, v190
	v_pk_add_f32 v[110:111], v[110:111], v[126:127]
	v_pk_add_f32 v[108:109], v[108:109], v[120:121]
	v_pk_add_f32 v[106:107], v[106:107], v[152:153]
	v_pk_add_f32 v[104:105], v[104:105], v[122:123]
	v_pk_add_f32 v[102:103], v[102:103], v[154:155]
	v_pk_add_f32 v[100:101], v[100:101], v[124:125]
	v_pk_add_f32 v[118:119], v[96:97], v[118:119]
	v_cvt_pk_bf16_f32 v96, v108, v109
	v_cvt_pk_bf16_f32 v97, v110, v111
	v_mul_f32_e32 v109, v109, v109
	v_mul_f32_e32 v111, v111, v111
	v_cvt_pk_bf16_f32 v120, v104, v105
	v_mul_f32_e32 v105, v105, v105
	v_mul_f32_e32 v115, v107, v107
	v_pk_add_f32 v[98:99], v[98:99], v[156:157]
	v_mul_f32_e32 v121, v101, v101
	v_mul_f32_e32 v122, v103, v103
	v_fmac_f32_e32 v109, v108, v108
	v_fmac_f32_e32 v111, v110, v110
	v_fmac_f32_e32 v105, v104, v104
	v_fmac_f32_e32 v115, v106, v106
	v_mul_f32_e32 v123, v119, v119
	v_mul_f32_e32 v124, v99, v99
	global_store_dwordx2 v[116:117], v[96:97], off
	v_fmac_f32_e32 v121, v100, v100
	v_fmac_f32_e32 v122, v102, v102
	v_add_f32_e32 v96, v109, v111
	v_add_f32_e32 v97, v105, v115
	v_fmac_f32_e32 v123, v118, v118
	v_fmac_f32_e32 v124, v98, v98
	v_add_f32_e32 v104, v121, v122
	v_add_f32_e32 v96, v96, v97
	v_add_f32_e32 v96, v96, v104
	v_add_f32_e32 v97, v123, v124
	v_add_f32_e32 v96, v96, v97
	ds_bpermute_b32 v97, v151, v96
	v_cvt_pk_bf16_f32 v100, v100, v101
	v_cvt_pk_bf16_f32 v101, v102, v103
	v_cvt_pk_bf16_f32 v121, v106, v107
	global_store_dwordx2 v[116:117], v[100:101], off offset:256
	s_waitcnt lgkmcnt(0)
	v_add_f32_e32 v96, v96, v97
	ds_bpermute_b32 v97, v114, v96
	v_cvt_pk_bf16_f32 v100, v118, v119
	v_cvt_pk_bf16_f32 v101, v98, v99
	global_store_dwordx2 v[116:117], v[120:121], off offset:32
	global_store_dwordx2 v[116:117], v[100:101], off offset:288
	s_and_saveexec_b64 s[34:35], s[2:3]
	s_cbranch_execz .LBB0_1552
	v_lshl_add_u64 v[98:99], v[112:113], 2, s[14:15]
	s_waitcnt lgkmcnt(0)
	v_add_f32_e32 v96, v96, v97
	global_atomic_add_f32 v[98:99], v96, off
.LBB0_1552:
	s_or_b64 exec, exec, s[34:35]
	v_or_b32_e32 v96, 32, v142
	s_waitcnt lgkmcnt(0)
	v_ashrrev_i32_e32 v97, 31, v96
	v_lshlrev_b64 v[98:99], 10, v[96:97]
	v_lshl_add_u64 v[98:99], v[98:99], 0, v[140:141]
	v_lshlrev_b64 v[98:99], 1, v[98:99]
	v_lshl_add_u64 v[100:101], s[28:29], 0, v[98:99]
	s_nop 0
	v_lshl_add_u64 v[98:99], s[26:27], 0, v[98:99]
	s_waitcnt vmcnt(31)
	v_and_b32_e32 v109, 0xffff0000, v193
	v_lshlrev_b32_e32 v108, 16, v193
	v_and_b32_e32 v103, 0xffff0000, v192
	v_lshlrev_b32_e32 v102, 16, v192
	s_waitcnt vmcnt(30)
	v_and_b32_e32 v111, 0xffff0000, v195
	v_lshlrev_b32_e32 v110, 16, v195
	v_and_b32_e32 v105, 0xffff0000, v194
	v_lshlrev_b32_e32 v104, 16, v194
	s_waitcnt vmcnt(29)
	v_and_b32_e32 v113, 0xffff0000, v197
	v_lshlrev_b32_e32 v112, 16, v197
	v_and_b32_e32 v107, 0xffff0000, v196
	v_lshlrev_b32_e32 v106, 16, v196
	s_waitcnt vmcnt(28)
	v_and_b32_e32 v117, 0xffff0000, v199
	v_lshlrev_b32_e32 v116, 16, v199
	v_and_b32_e32 v101, 0xffff0000, v198
	v_lshlrev_b32_e32 v100, 16, v198
	v_pk_add_f32 v[94:95], v[94:95], v[108:109]
	v_pk_add_f32 v[92:93], v[92:93], v[102:103]
	v_pk_add_f32 v[90:91], v[90:91], v[110:111]
	v_pk_add_f32 v[88:89], v[88:89], v[104:105]
	v_pk_add_f32 v[86:87], v[86:87], v[112:113]
	v_pk_add_f32 v[84:85], v[84:85], v[106:107]
	v_pk_add_f32 v[100:101], v[80:81], v[100:101]
	v_cvt_pk_bf16_f32 v80, v92, v93
	v_cvt_pk_bf16_f32 v81, v94, v95
	v_mul_f32_e32 v93, v93, v93
	v_mul_f32_e32 v95, v95, v95
	v_cvt_pk_bf16_f32 v102, v88, v89
	v_mul_f32_e32 v89, v89, v89
	v_mul_f32_e32 v103, v91, v91
	v_pk_add_f32 v[82:83], v[82:83], v[116:117]
	v_mul_f32_e32 v104, v85, v85
	v_mul_f32_e32 v105, v87, v87
	v_fmac_f32_e32 v93, v92, v92
	v_fmac_f32_e32 v95, v94, v94
	v_fmac_f32_e32 v89, v88, v88
	v_fmac_f32_e32 v103, v90, v90
	v_mul_f32_e32 v106, v101, v101
	v_mul_f32_e32 v107, v83, v83
	global_store_dwordx2 v[98:99], v[80:81], off
	v_fmac_f32_e32 v104, v84, v84
	v_fmac_f32_e32 v105, v86, v86
	v_add_f32_e32 v80, v93, v95
	v_add_f32_e32 v81, v89, v103
	v_fmac_f32_e32 v106, v100, v100
	v_fmac_f32_e32 v107, v82, v82
	v_add_f32_e32 v88, v104, v105
	v_add_f32_e32 v80, v80, v81
	v_add_f32_e32 v80, v80, v88
	v_add_f32_e32 v81, v106, v107
	v_add_f32_e32 v80, v80, v81
	ds_bpermute_b32 v81, v151, v80
	v_cvt_pk_bf16_f32 v84, v84, v85
	v_cvt_pk_bf16_f32 v85, v86, v87
	v_cvt_pk_bf16_f32 v103, v90, v91
	global_store_dwordx2 v[98:99], v[84:85], off offset:256
	s_waitcnt lgkmcnt(0)
	v_add_f32_e32 v80, v80, v81
	ds_bpermute_b32 v81, v114, v80
	v_cvt_pk_bf16_f32 v84, v100, v101
	v_cvt_pk_bf16_f32 v85, v82, v83
	global_store_dwordx2 v[98:99], v[102:103], off offset:32
	global_store_dwordx2 v[98:99], v[84:85], off offset:288
	s_and_saveexec_b64 s[34:35], s[2:3]
	s_cbranch_execz .LBB0_1554
	v_lshl_add_u64 v[82:83], v[96:97], 2, s[14:15]
	s_waitcnt lgkmcnt(0)
	v_add_f32_e32 v80, v80, v81
	global_atomic_add_f32 v[82:83], v80, off
.LBB0_1554:
	s_or_b64 exec, exec, s[34:35]
	v_or_b32_e32 v80, 48, v142
	s_waitcnt lgkmcnt(0)
	v_ashrrev_i32_e32 v81, 31, v80
	v_lshlrev_b64 v[82:83], 10, v[80:81]
	v_lshl_add_u64 v[82:83], v[82:83], 0, v[140:141]
	v_lshlrev_b64 v[82:83], 1, v[82:83]
	v_lshl_add_u64 v[84:85], s[28:29], 0, v[82:83]
	s_nop 0
	v_lshl_add_u64 v[82:83], s[26:27], 0, v[82:83]
	s_waitcnt vmcnt(31)
	v_and_b32_e32 v93, 0xffff0000, v201
	v_lshlrev_b32_e32 v92, 16, v201
	v_and_b32_e32 v87, 0xffff0000, v200
	v_lshlrev_b32_e32 v86, 16, v200
	s_waitcnt vmcnt(30)
	v_and_b32_e32 v95, 0xffff0000, v203
	v_lshlrev_b32_e32 v94, 16, v203
	v_and_b32_e32 v89, 0xffff0000, v202
	v_lshlrev_b32_e32 v88, 16, v202
	s_waitcnt vmcnt(29)
	v_and_b32_e32 v97, 0xffff0000, v205
	v_lshlrev_b32_e32 v96, 16, v205
	v_and_b32_e32 v91, 0xffff0000, v204
	v_lshlrev_b32_e32 v90, 16, v204
	s_waitcnt vmcnt(28)
	v_and_b32_e32 v99, 0xffff0000, v207
	v_lshlrev_b32_e32 v98, 16, v207
	v_and_b32_e32 v85, 0xffff0000, v206
	v_lshlrev_b32_e32 v84, 16, v206
	v_pk_add_f32 v[78:79], v[78:79], v[92:93]
	v_pk_add_f32 v[76:77], v[76:77], v[86:87]
	v_pk_add_f32 v[74:75], v[74:75], v[94:95]
	v_pk_add_f32 v[72:73], v[72:73], v[88:89]
	v_pk_add_f32 v[70:71], v[70:71], v[96:97]
	v_pk_add_f32 v[68:69], v[68:69], v[90:91]
	v_pk_add_f32 v[84:85], v[64:65], v[84:85]
	v_cvt_pk_bf16_f32 v64, v76, v77
	v_cvt_pk_bf16_f32 v65, v78, v79
	v_mul_f32_e32 v77, v77, v77
	v_mul_f32_e32 v79, v79, v79
	v_cvt_pk_bf16_f32 v86, v72, v73
	v_mul_f32_e32 v73, v73, v73
	v_mul_f32_e32 v87, v75, v75
	v_pk_add_f32 v[66:67], v[66:67], v[98:99]
	v_mul_f32_e32 v88, v69, v69
	v_mul_f32_e32 v89, v71, v71
	v_fmac_f32_e32 v77, v76, v76
	v_fmac_f32_e32 v79, v78, v78
	v_fmac_f32_e32 v73, v72, v72
	v_fmac_f32_e32 v87, v74, v74
	v_mul_f32_e32 v90, v85, v85
	v_mul_f32_e32 v91, v67, v67
	global_store_dwordx2 v[82:83], v[64:65], off
	v_fmac_f32_e32 v88, v68, v68
	v_fmac_f32_e32 v89, v70, v70
	v_add_f32_e32 v64, v77, v79
	v_add_f32_e32 v65, v73, v87
	v_fmac_f32_e32 v90, v84, v84
	v_fmac_f32_e32 v91, v66, v66
	v_add_f32_e32 v72, v88, v89
	v_add_f32_e32 v64, v64, v65
	v_add_f32_e32 v64, v64, v72
	v_add_f32_e32 v65, v90, v91
	v_add_f32_e32 v64, v64, v65
	ds_bpermute_b32 v65, v151, v64
	v_cvt_pk_bf16_f32 v68, v68, v69
	v_cvt_pk_bf16_f32 v69, v70, v71
	v_cvt_pk_bf16_f32 v87, v74, v75
	global_store_dwordx2 v[82:83], v[68:69], off offset:256
	s_waitcnt lgkmcnt(0)
	v_add_f32_e32 v64, v64, v65
	ds_bpermute_b32 v65, v114, v64
	v_cvt_pk_bf16_f32 v68, v84, v85
	v_cvt_pk_bf16_f32 v69, v66, v67
	global_store_dwordx2 v[82:83], v[86:87], off offset:32
	global_store_dwordx2 v[82:83], v[68:69], off offset:288
	s_and_saveexec_b64 s[34:35], s[2:3]
	s_cbranch_execz .LBB0_1556
	v_lshl_add_u64 v[66:67], v[80:81], 2, s[14:15]
	s_waitcnt lgkmcnt(0)
	v_add_f32_e32 v64, v64, v65
	global_atomic_add_f32 v[66:67], v64, off
.LBB0_1556:
	s_or_b64 exec, exec, s[34:35]
	v_add_u32_e32 v64, 0x80, v142
	s_waitcnt lgkmcnt(0)
	v_ashrrev_i32_e32 v65, 31, v64
	v_lshlrev_b64 v[66:67], 10, v[64:65]
	v_lshl_add_u64 v[66:67], v[66:67], 0, v[140:141]
	v_lshlrev_b64 v[66:67], 1, v[66:67]
	v_lshl_add_u64 v[68:69], s[28:29], 0, v[66:67]
	s_nop 0
	v_lshl_add_u64 v[66:67], s[26:27], 0, v[66:67]
	s_waitcnt vmcnt(31)
	v_and_b32_e32 v77, 0xffff0000, v209
	v_lshlrev_b32_e32 v76, 16, v209
	v_and_b32_e32 v71, 0xffff0000, v208
	v_lshlrev_b32_e32 v70, 16, v208
	s_waitcnt vmcnt(30)
	v_and_b32_e32 v79, 0xffff0000, v211
	v_lshlrev_b32_e32 v78, 16, v211
	v_and_b32_e32 v73, 0xffff0000, v210
	v_lshlrev_b32_e32 v72, 16, v210
	s_waitcnt vmcnt(29)
	v_and_b32_e32 v81, 0xffff0000, v223
	v_lshlrev_b32_e32 v80, 16, v223
	v_and_b32_e32 v75, 0xffff0000, v222
	v_lshlrev_b32_e32 v74, 16, v222
	s_waitcnt vmcnt(28)
	v_and_b32_e32 v83, 0xffff0000, v225
	v_lshlrev_b32_e32 v82, 16, v225
	v_and_b32_e32 v69, 0xffff0000, v224
	v_lshlrev_b32_e32 v68, 16, v224
	v_pk_add_f32 v[62:63], v[62:63], v[76:77]
	v_pk_add_f32 v[60:61], v[60:61], v[70:71]
	v_pk_add_f32 v[58:59], v[58:59], v[78:79]
	v_pk_add_f32 v[56:57], v[56:57], v[72:73]
	v_pk_add_f32 v[54:55], v[54:55], v[80:81]
	v_pk_add_f32 v[52:53], v[52:53], v[74:75]
	v_pk_add_f32 v[68:69], v[48:49], v[68:69]
	v_cvt_pk_bf16_f32 v48, v60, v61
	v_cvt_pk_bf16_f32 v49, v62, v63
	v_mul_f32_e32 v61, v61, v61
	v_mul_f32_e32 v63, v63, v63
	v_cvt_pk_bf16_f32 v70, v56, v57
	v_mul_f32_e32 v57, v57, v57
	v_mul_f32_e32 v71, v59, v59
	v_pk_add_f32 v[50:51], v[50:51], v[82:83]
	v_mul_f32_e32 v72, v53, v53
	v_mul_f32_e32 v73, v55, v55
	v_fmac_f32_e32 v61, v60, v60
	v_fmac_f32_e32 v63, v62, v62
	v_fmac_f32_e32 v57, v56, v56
	v_fmac_f32_e32 v71, v58, v58
	v_mul_f32_e32 v74, v69, v69
	v_mul_f32_e32 v75, v51, v51
	global_store_dwordx2 v[66:67], v[48:49], off
	v_fmac_f32_e32 v72, v52, v52
	v_fmac_f32_e32 v73, v54, v54
	v_add_f32_e32 v48, v61, v63
	v_add_f32_e32 v49, v57, v71
	v_fmac_f32_e32 v74, v68, v68
	v_fmac_f32_e32 v75, v50, v50
	v_add_f32_e32 v56, v72, v73
	v_add_f32_e32 v48, v48, v49
	v_add_f32_e32 v48, v48, v56
	v_add_f32_e32 v49, v74, v75
	v_add_f32_e32 v48, v48, v49
	ds_bpermute_b32 v49, v151, v48
	v_cvt_pk_bf16_f32 v52, v52, v53
	v_cvt_pk_bf16_f32 v53, v54, v55
	v_cvt_pk_bf16_f32 v71, v58, v59
	global_store_dwordx2 v[66:67], v[52:53], off offset:256
	s_waitcnt lgkmcnt(0)
	v_add_f32_e32 v48, v48, v49
	ds_bpermute_b32 v49, v114, v48
	v_cvt_pk_bf16_f32 v52, v68, v69
	v_cvt_pk_bf16_f32 v53, v50, v51
	global_store_dwordx2 v[66:67], v[70:71], off offset:32
	global_store_dwordx2 v[66:67], v[52:53], off offset:288
	s_and_saveexec_b64 s[34:35], s[2:3]
	s_cbranch_execz .LBB0_1558
	v_lshl_add_u64 v[50:51], v[64:65], 2, s[14:15]
	s_waitcnt lgkmcnt(0)
	v_add_f32_e32 v48, v48, v49
	global_atomic_add_f32 v[50:51], v48, off
.LBB0_1558:
	s_or_b64 exec, exec, s[34:35]
	v_add_u32_e32 v48, 0x90, v142
	s_waitcnt lgkmcnt(0)
	v_ashrrev_i32_e32 v49, 31, v48
	v_lshlrev_b64 v[50:51], 10, v[48:49]
	v_lshl_add_u64 v[50:51], v[50:51], 0, v[140:141]
	v_lshlrev_b64 v[50:51], 1, v[50:51]
	v_lshl_add_u64 v[52:53], s[28:29], 0, v[50:51]
	s_nop 0
	v_lshl_add_u64 v[50:51], s[26:27], 0, v[50:51]
	s_waitcnt vmcnt(31)
	v_and_b32_e32 v61, 0xffff0000, v227
	v_lshlrev_b32_e32 v60, 16, v227
	v_and_b32_e32 v55, 0xffff0000, v226
	v_lshlrev_b32_e32 v54, 16, v226
	s_waitcnt vmcnt(30)
	v_and_b32_e32 v63, 0xffff0000, v229
	v_lshlrev_b32_e32 v62, 16, v229
	v_and_b32_e32 v57, 0xffff0000, v228
	v_lshlrev_b32_e32 v56, 16, v228
	s_waitcnt vmcnt(29)
	v_and_b32_e32 v65, 0xffff0000, v231
	v_lshlrev_b32_e32 v64, 16, v231
	v_and_b32_e32 v59, 0xffff0000, v230
	v_lshlrev_b32_e32 v58, 16, v230
	s_waitcnt vmcnt(28)
	v_and_b32_e32 v67, 0xffff0000, v233
	v_lshlrev_b32_e32 v66, 16, v233
	v_and_b32_e32 v53, 0xffff0000, v232
	v_lshlrev_b32_e32 v52, 16, v232
	v_pk_add_f32 v[46:47], v[46:47], v[60:61]
	v_pk_add_f32 v[44:45], v[44:45], v[54:55]
	v_pk_add_f32 v[42:43], v[42:43], v[62:63]
	v_pk_add_f32 v[40:41], v[40:41], v[56:57]
	v_pk_add_f32 v[38:39], v[38:39], v[64:65]
	v_pk_add_f32 v[36:37], v[36:37], v[58:59]
	v_pk_add_f32 v[52:53], v[32:33], v[52:53]
	v_cvt_pk_bf16_f32 v32, v44, v45
	v_cvt_pk_bf16_f32 v33, v46, v47
	v_mul_f32_e32 v45, v45, v45
	v_mul_f32_e32 v47, v47, v47
	v_cvt_pk_bf16_f32 v54, v40, v41
	v_mul_f32_e32 v41, v41, v41
	v_mul_f32_e32 v55, v43, v43
	v_pk_add_f32 v[34:35], v[34:35], v[66:67]
	v_mul_f32_e32 v56, v37, v37
	v_mul_f32_e32 v57, v39, v39
	v_fmac_f32_e32 v45, v44, v44
	v_fmac_f32_e32 v47, v46, v46
	v_fmac_f32_e32 v41, v40, v40
	v_fmac_f32_e32 v55, v42, v42
	v_mul_f32_e32 v58, v53, v53
	v_mul_f32_e32 v59, v35, v35
	global_store_dwordx2 v[50:51], v[32:33], off
	v_fmac_f32_e32 v56, v36, v36
	v_fmac_f32_e32 v57, v38, v38
	v_add_f32_e32 v32, v45, v47
	v_add_f32_e32 v33, v41, v55
	v_fmac_f32_e32 v58, v52, v52
	v_fmac_f32_e32 v59, v34, v34
	v_add_f32_e32 v40, v56, v57
	v_add_f32_e32 v32, v32, v33
	v_add_f32_e32 v32, v32, v40
	v_add_f32_e32 v33, v58, v59
	v_add_f32_e32 v32, v32, v33
	ds_bpermute_b32 v33, v151, v32
	v_cvt_pk_bf16_f32 v36, v36, v37
	v_cvt_pk_bf16_f32 v37, v38, v39
	v_cvt_pk_bf16_f32 v55, v42, v43
	global_store_dwordx2 v[50:51], v[36:37], off offset:256
	s_waitcnt lgkmcnt(0)
	v_add_f32_e32 v32, v32, v33
	ds_bpermute_b32 v33, v114, v32
	v_cvt_pk_bf16_f32 v36, v52, v53
	v_cvt_pk_bf16_f32 v37, v34, v35
	global_store_dwordx2 v[50:51], v[54:55], off offset:32
	global_store_dwordx2 v[50:51], v[36:37], off offset:288
	s_and_saveexec_b64 s[34:35], s[2:3]
	s_cbranch_execz .LBB0_1560
	v_lshl_add_u64 v[34:35], v[48:49], 2, s[14:15]
	s_waitcnt lgkmcnt(0)
	v_add_f32_e32 v32, v32, v33
	global_atomic_add_f32 v[34:35], v32, off
.LBB0_1560:
	s_or_b64 exec, exec, s[34:35]
	v_add_u32_e32 v32, 0xa0, v142
	s_waitcnt lgkmcnt(0)
	v_ashrrev_i32_e32 v33, 31, v32
	v_lshlrev_b64 v[34:35], 10, v[32:33]
	v_lshl_add_u64 v[34:35], v[34:35], 0, v[140:141]
	v_lshlrev_b64 v[34:35], 1, v[34:35]
	v_lshl_add_u64 v[36:37], s[28:29], 0, v[34:35]
	s_nop 0
	v_lshl_add_u64 v[34:35], s[26:27], 0, v[34:35]
	s_waitcnt vmcnt(31)
	v_and_b32_e32 v45, 0xffff0000, v235
	v_lshlrev_b32_e32 v44, 16, v235
	v_and_b32_e32 v39, 0xffff0000, v234
	v_lshlrev_b32_e32 v38, 16, v234
	s_waitcnt vmcnt(30)
	v_and_b32_e32 v47, 0xffff0000, v237
	v_lshlrev_b32_e32 v46, 16, v237
	v_and_b32_e32 v41, 0xffff0000, v236
	v_lshlrev_b32_e32 v40, 16, v236
	s_waitcnt vmcnt(29)
	v_and_b32_e32 v49, 0xffff0000, v239
	v_lshlrev_b32_e32 v48, 16, v239
	v_and_b32_e32 v43, 0xffff0000, v238
	v_lshlrev_b32_e32 v42, 16, v238
	s_waitcnt vmcnt(28)
	v_and_b32_e32 v51, 0xffff0000, v241
	v_lshlrev_b32_e32 v50, 16, v241
	v_and_b32_e32 v37, 0xffff0000, v240
	v_lshlrev_b32_e32 v36, 16, v240
	v_pk_add_f32 v[30:31], v[30:31], v[44:45]
	v_pk_add_f32 v[28:29], v[28:29], v[38:39]
	v_pk_add_f32 v[26:27], v[26:27], v[46:47]
	v_pk_add_f32 v[24:25], v[24:25], v[40:41]
	v_pk_add_f32 v[22:23], v[22:23], v[48:49]
	v_pk_add_f32 v[20:21], v[20:21], v[42:43]
	v_pk_add_f32 v[36:37], v[16:17], v[36:37]
	v_cvt_pk_bf16_f32 v16, v28, v29
	v_cvt_pk_bf16_f32 v17, v30, v31
	v_mul_f32_e32 v29, v29, v29
	v_mul_f32_e32 v31, v31, v31
	v_cvt_pk_bf16_f32 v38, v24, v25
	v_mul_f32_e32 v25, v25, v25
	v_mul_f32_e32 v39, v27, v27
	v_pk_add_f32 v[18:19], v[18:19], v[50:51]
	v_mul_f32_e32 v40, v21, v21
	v_mul_f32_e32 v41, v23, v23
	v_fmac_f32_e32 v29, v28, v28
	v_fmac_f32_e32 v31, v30, v30
	v_fmac_f32_e32 v25, v24, v24
	v_fmac_f32_e32 v39, v26, v26
	v_mul_f32_e32 v42, v37, v37
	v_mul_f32_e32 v43, v19, v19
	global_store_dwordx2 v[34:35], v[16:17], off
	v_fmac_f32_e32 v40, v20, v20
	v_fmac_f32_e32 v41, v22, v22
	v_add_f32_e32 v16, v29, v31
	v_add_f32_e32 v17, v25, v39
	v_fmac_f32_e32 v42, v36, v36
	v_fmac_f32_e32 v43, v18, v18
	v_add_f32_e32 v24, v40, v41
	v_add_f32_e32 v16, v16, v17
	v_add_f32_e32 v16, v16, v24
	v_add_f32_e32 v17, v42, v43
	v_add_f32_e32 v16, v16, v17
	ds_bpermute_b32 v17, v151, v16
	v_cvt_pk_bf16_f32 v20, v20, v21
	v_cvt_pk_bf16_f32 v21, v22, v23
	v_cvt_pk_bf16_f32 v39, v26, v27
	global_store_dwordx2 v[34:35], v[20:21], off offset:256
	s_waitcnt lgkmcnt(0)
	v_add_f32_e32 v16, v16, v17
	ds_bpermute_b32 v17, v114, v16
	v_cvt_pk_bf16_f32 v20, v36, v37
	v_cvt_pk_bf16_f32 v21, v18, v19
	global_store_dwordx2 v[34:35], v[38:39], off offset:32
	global_store_dwordx2 v[34:35], v[20:21], off offset:288
	s_and_saveexec_b64 s[34:35], s[2:3]
	s_cbranch_execz .LBB0_1562
	v_lshl_add_u64 v[18:19], v[32:33], 2, s[14:15]
	s_waitcnt lgkmcnt(0)
	v_add_f32_e32 v16, v16, v17
	global_atomic_add_f32 v[18:19], v16, off
.LBB0_1562:
	s_or_b64 exec, exec, s[34:35]
	v_add_u32_e32 v16, 0xb0, v142
	s_waitcnt lgkmcnt(0)
	v_ashrrev_i32_e32 v17, 31, v16
	v_lshlrev_b64 v[18:19], 10, v[16:17]
	v_lshl_add_u64 v[18:19], v[18:19], 0, v[140:141]
	v_lshlrev_b64 v[18:19], 1, v[18:19]
	v_lshl_add_u64 v[20:21], s[28:29], 0, v[18:19]
	s_nop 0
	v_lshl_add_u64 v[18:19], s[26:27], 0, v[18:19]
	s_waitcnt vmcnt(31)
	v_and_b32_e32 v29, 0xffff0000, v243
	v_lshlrev_b32_e32 v28, 16, v243
	v_and_b32_e32 v23, 0xffff0000, v242
	v_lshlrev_b32_e32 v22, 16, v242
	s_waitcnt vmcnt(30)
	v_and_b32_e32 v31, 0xffff0000, v245
	v_lshlrev_b32_e32 v30, 16, v245
	v_and_b32_e32 v25, 0xffff0000, v244
	v_lshlrev_b32_e32 v24, 16, v244
	s_waitcnt vmcnt(29)
	v_and_b32_e32 v33, 0xffff0000, v247
	v_lshlrev_b32_e32 v32, 16, v247
	v_and_b32_e32 v27, 0xffff0000, v246
	v_lshlrev_b32_e32 v26, 16, v246
	s_waitcnt vmcnt(28)
	v_and_b32_e32 v35, 0xffff0000, v249
	v_lshlrev_b32_e32 v34, 16, v249
	v_and_b32_e32 v21, 0xffff0000, v248
	v_lshlrev_b32_e32 v20, 16, v248
	v_pk_add_f32 v[14:15], v[14:15], v[28:29]
	v_pk_add_f32 v[12:13], v[12:13], v[22:23]
	v_pk_add_f32 v[10:11], v[10:11], v[30:31]
	v_pk_add_f32 v[8:9], v[8:9], v[24:25]
	v_pk_add_f32 v[6:7], v[6:7], v[32:33]
	v_pk_add_f32 v[4:5], v[4:5], v[26:27]
	v_pk_add_f32 v[20:21], v[0:1], v[20:21]
	v_cvt_pk_bf16_f32 v0, v12, v13
	v_cvt_pk_bf16_f32 v1, v14, v15
	v_mul_f32_e32 v13, v13, v13
	v_mul_f32_e32 v15, v15, v15
	v_cvt_pk_bf16_f32 v22, v8, v9
	v_mul_f32_e32 v9, v9, v9
	v_mul_f32_e32 v23, v11, v11
	v_pk_add_f32 v[2:3], v[2:3], v[34:35]
	v_mul_f32_e32 v24, v5, v5
	v_mul_f32_e32 v25, v7, v7
	v_fmac_f32_e32 v13, v12, v12
	v_fmac_f32_e32 v15, v14, v14
	v_fmac_f32_e32 v9, v8, v8
	v_fmac_f32_e32 v23, v10, v10
	v_mul_f32_e32 v26, v21, v21
	v_mul_f32_e32 v27, v3, v3
	global_store_dwordx2 v[18:19], v[0:1], off
	v_fmac_f32_e32 v24, v4, v4
	v_fmac_f32_e32 v25, v6, v6
	v_add_f32_e32 v0, v13, v15
	v_add_f32_e32 v1, v9, v23
	v_fmac_f32_e32 v26, v20, v20
	v_fmac_f32_e32 v27, v2, v2
	v_add_f32_e32 v8, v24, v25
	v_add_f32_e32 v0, v0, v1
	v_add_f32_e32 v0, v0, v8
	v_add_f32_e32 v1, v26, v27
	v_add_f32_e32 v0, v0, v1
	ds_bpermute_b32 v1, v151, v0
	v_cvt_pk_bf16_f32 v4, v4, v5
	v_cvt_pk_bf16_f32 v5, v6, v7
	v_cvt_pk_bf16_f32 v23, v10, v11
	global_store_dwordx2 v[18:19], v[4:5], off offset:256
	s_waitcnt lgkmcnt(0)
	v_add_f32_e32 v0, v0, v1
	ds_bpermute_b32 v1, v114, v0
	v_cvt_pk_bf16_f32 v4, v20, v21
	v_cvt_pk_bf16_f32 v5, v2, v3
	global_store_dwordx2 v[18:19], v[22:23], off offset:32
	global_store_dwordx2 v[18:19], v[4:5], off offset:288
	s_and_saveexec_b64 s[34:35], s[2:3]
	s_cbranch_execz .LBB0_1564
	v_lshl_add_u64 v[2:3], v[16:17], 2, s[14:15]
	s_waitcnt lgkmcnt(0)
	v_add_f32_e32 v0, v0, v1
	global_atomic_add_f32 v[2:3], v0, off

.LBB0_1817:
	v_lshl_add_u32 v142, s38, 8, v144
	v_lshl_add_u32 v140, s40, 8, v146
	v_ashrrev_i32_e32 v143, 31, v142
	v_ashrrev_i32_e32 v141, 31, v140
	v_lshlrev_b64 v[152:153], 10, v[142:143]
	v_lshl_add_u64 v[152:153], v[152:153], 0, v[140:141]
	v_lshl_add_u64 v[152:153], v[152:153], 1, s[26:27]
	v_add_u32_e32 v252, 0x0, v142
	v_ashrrev_i32_e32 v253, 31, v252
	v_lshlrev_b64 v[252:253], 10, v[252:253]
	v_lshl_add_u64 v[252:253], v[252:253], 0, v[140:141]
	v_lshl_add_u64 v[252:253], v[252:253], 1, s[26:27]
	global_load_dwordx2 v[172:173], v[252:253], off
	global_load_dwordx2 v[174:175], v[252:253], off offset:32
	global_load_dwordx2 v[176:177], v[252:253], off offset:256
	global_load_dwordx2 v[178:179], v[252:253], off offset:288
	v_add_u32_e32 v250, 0x10, v142
	v_ashrrev_i32_e32 v251, 31, v250
	v_lshlrev_b64 v[250:251], 10, v[250:251]
	v_lshl_add_u64 v[250:251], v[250:251], 0, v[140:141]
	v_lshl_add_u64 v[250:251], v[250:251], 1, s[26:27]
	global_load_dwordx2 v[180:181], v[250:251], off
	global_load_dwordx2 v[182:183], v[250:251], off offset:32
	global_load_dwordx2 v[184:185], v[250:251], off offset:256
	global_load_dwordx2 v[186:187], v[250:251], off offset:288
	v_add_u32_e32 v252, 0x20, v142
	v_ashrrev_i32_e32 v253, 31, v252
	v_lshlrev_b64 v[252:253], 10, v[252:253]
	v_lshl_add_u64 v[252:253], v[252:253], 0, v[140:141]
	v_lshl_add_u64 v[252:253], v[252:253], 1, s[26:27]
	global_load_dwordx2 v[188:189], v[252:253], off
	global_load_dwordx2 v[190:191], v[252:253], off offset:32
	global_load_dwordx2 v[192:193], v[252:253], off offset:256
	global_load_dwordx2 v[194:195], v[252:253], off offset:288
	v_add_u32_e32 v250, 0x30, v142
	v_ashrrev_i32_e32 v251, 31, v250
	v_lshlrev_b64 v[250:251], 10, v[250:251]
	v_lshl_add_u64 v[250:251], v[250:251], 0, v[140:141]
	v_lshl_add_u64 v[250:251], v[250:251], 1, s[26:27]
	global_load_dwordx2 v[196:197], v[250:251], off
	global_load_dwordx2 v[198:199], v[250:251], off offset:32
	global_load_dwordx2 v[200:201], v[250:251], off offset:256
	global_load_dwordx2 v[202:203], v[250:251], off offset:288
	v_add_u32_e32 v252, 0x80, v142
	v_ashrrev_i32_e32 v253, 31, v252
	v_lshlrev_b64 v[252:253], 10, v[252:253]
	v_lshl_add_u64 v[252:253], v[252:253], 0, v[140:141]
	v_lshl_add_u64 v[252:253], v[252:253], 1, s[26:27]
	global_load_dwordx2 v[204:205], v[252:253], off
	global_load_dwordx2 v[206:207], v[252:253], off offset:32
	global_load_dwordx2 v[208:209], v[252:253], off offset:256
	global_load_dwordx2 v[210:211], v[252:253], off offset:288
	v_add_u32_e32 v250, 0x90, v142
	v_ashrrev_i32_e32 v251, 31, v250
	v_lshlrev_b64 v[250:251], 10, v[250:251]
	v_lshl_add_u64 v[250:251], v[250:251], 0, v[140:141]
	v_lshl_add_u64 v[250:251], v[250:251], 1, s[26:27]
	global_load_dwordx2 v[212:213], v[250:251], off
	global_load_dwordx2 v[214:215], v[250:251], off offset:32
	global_load_dwordx2 v[222:223], v[250:251], off offset:256
	global_load_dwordx2 v[224:225], v[250:251], off offset:288
	v_add_u32_e32 v252, 0xa0, v142
	v_ashrrev_i32_e32 v253, 31, v252
	v_lshlrev_b64 v[252:253], 10, v[252:253]
	v_lshl_add_u64 v[252:253], v[252:253], 0, v[140:141]
	v_lshl_add_u64 v[252:253], v[252:253], 1, s[26:27]
	global_load_dwordx2 v[226:227], v[252:253], off
	global_load_dwordx2 v[228:229], v[252:253], off offset:32
	global_load_dwordx2 v[230:231], v[252:253], off offset:256
	global_load_dwordx2 v[232:233], v[252:253], off offset:288
	v_add_u32_e32 v250, 0xb0, v142
	v_ashrrev_i32_e32 v251, 31, v250
	v_lshlrev_b64 v[250:251], 10, v[250:251]
	v_lshl_add_u64 v[250:251], v[250:251], 0, v[140:141]
	v_lshl_add_u64 v[250:251], v[250:251], 1, s[26:27]
	global_load_dwordx2 v[234:235], v[250:251], off
	global_load_dwordx2 v[236:237], v[250:251], off offset:32
	global_load_dwordx2 v[238:239], v[250:251], off offset:256
	global_load_dwordx2 v[240:241], v[250:251], off offset:288
	v_and_b32_e32 v162, 64, v150
	v_xor_b32_e32 v151, 16, v150
	v_add_u32_e32 v162, 64, v162
	v_xor_b32_e32 v163, 32, v150
	v_cmp_lt_i32_e32 vcc, v151, v162
	s_waitcnt vmcnt(28)
	v_and_b32_e32 v165, 0xffff0000, v175
	v_cndmask_b32_e32 v151, v150, v151, vcc
	v_cmp_lt_i32_e32 vcc, v163, v162
	v_lshlrev_b32_e32 v162, 16, v173
	v_lshlrev_b32_e32 v164, 16, v175
	v_cndmask_b32_e32 v170, v150, v163, vcc
	v_and_b32_e32 v163, 0xffff0000, v173
	v_and_b32_e32 v155, 0xffff0000, v172
	v_lshlrev_b32_e32 v154, 16, v172
	v_and_b32_e32 v157, 0xffff0000, v174
	v_lshlrev_b32_e32 v156, 16, v174
	v_and_b32_e32 v167, 0xffff0000, v177
	v_lshlrev_b32_e32 v166, 16, v177
	v_and_b32_e32 v159, 0xffff0000, v176
	v_lshlrev_b32_e32 v158, 16, v176
	v_and_b32_e32 v169, 0xffff0000, v179
	v_lshlrev_b32_e32 v168, 16, v179
	v_and_b32_e32 v161, 0xffff0000, v178
	v_lshlrev_b32_e32 v160, 16, v178
	v_pk_add_f32 v[126:127], v[126:127], v[162:163]
	v_pk_add_f32 v[124:125], v[124:125], v[154:155]
	v_pk_add_f32 v[122:123], v[122:123], v[164:165]
	v_pk_add_f32 v[120:121], v[120:121], v[156:157]
	v_pk_add_f32 v[118:119], v[118:119], v[166:167]
	v_pk_add_f32 v[116:117], v[116:117], v[158:159]
	v_pk_add_f32 v[154:155], v[114:115], v[168:169]
	v_pk_add_f32 v[156:157], v[112:113], v[160:161]
	v_cvt_pk_bf16_f32 v112, v124, v125
	v_cvt_pk_bf16_f32 v113, v126, v127
	v_mul_f32_e32 v125, v125, v125
	v_mul_f32_e32 v127, v127, v127
	v_cvt_pk_bf16_f32 v114, v120, v121
	v_cvt_pk_bf16_f32 v115, v122, v123
	v_mul_f32_e32 v121, v121, v121
	v_mul_f32_e32 v123, v123, v123
	v_mul_f32_e32 v158, v117, v117
	v_mul_f32_e32 v159, v119, v119
	v_fmac_f32_e32 v125, v124, v124
	v_fmac_f32_e32 v127, v126, v126
	v_fmac_f32_e32 v121, v120, v120
	v_fmac_f32_e32 v123, v122, v122
	v_mul_f32_e32 v160, v157, v157
	v_mul_f32_e32 v161, v155, v155
	v_fmac_f32_e32 v158, v116, v116
	v_fmac_f32_e32 v159, v118, v118
	v_add_f32_e32 v120, v125, v127
	v_add_f32_e32 v121, v121, v123
	v_fmac_f32_e32 v160, v156, v156
	v_fmac_f32_e32 v161, v154, v154
	v_add_f32_e32 v122, v158, v159
	v_add_f32_e32 v120, v120, v121
	v_add_f32_e32 v123, v160, v161
	v_add_f32_e32 v120, v120, v122
	v_lshlrev_b32_e32 v151, 2, v151
	v_add_f32_e32 v120, v120, v123
	ds_bpermute_b32 v121, v151, v120
	global_store_dwordx2 v[152:153], v[112:113], off
	global_store_dwordx2 v[152:153], v[114:115], off offset:32
	v_lshlrev_b32_e32 v114, 2, v170
	v_cvt_pk_bf16_f32 v116, v116, v117
	v_cvt_pk_bf16_f32 v117, v118, v119
	s_waitcnt lgkmcnt(0)
	v_add_f32_e32 v112, v120, v121
	ds_bpermute_b32 v113, v114, v112
	global_store_dwordx2 v[152:153], v[116:117], off offset:256
	v_cvt_pk_bf16_f32 v116, v156, v157
	v_cvt_pk_bf16_f32 v117, v154, v155
	global_store_dwordx2 v[152:153], v[116:117], off offset:288
	s_and_saveexec_b64 s[38:39], s[2:3]
	s_cbranch_execz .LBB0_1819
	v_lshl_add_u64 v[116:117], v[142:143], 2, s[12:13]
	s_waitcnt lgkmcnt(0)
	v_add_f32_e32 v112, v112, v113
	global_atomic_add_f32 v[116:117], v112, off
.LBB0_1819:
	s_or_b64 exec, exec, s[38:39]
	v_or_b32_e32 v112, 16, v142
	s_waitcnt lgkmcnt(0)
	v_ashrrev_i32_e32 v113, 31, v112
	v_lshlrev_b64 v[116:117], 10, v[112:113]
	v_lshl_add_u64 v[116:117], v[116:117], 0, v[140:141]
	v_lshl_add_u64 v[116:117], v[116:117], 1, s[26:27]
	s_waitcnt vmcnt(31)
	v_and_b32_e32 v127, 0xffff0000, v181
	v_lshlrev_b32_e32 v126, 16, v181
	v_and_b32_e32 v119, 0xffff0000, v180
	v_lshlrev_b32_e32 v118, 16, v180
	s_waitcnt vmcnt(30)
	v_and_b32_e32 v153, 0xffff0000, v183
	v_lshlrev_b32_e32 v152, 16, v183
	v_and_b32_e32 v121, 0xffff0000, v182
	v_lshlrev_b32_e32 v120, 16, v182
	s_waitcnt vmcnt(29)
	v_and_b32_e32 v155, 0xffff0000, v185
	v_lshlrev_b32_e32 v154, 16, v185
	v_and_b32_e32 v123, 0xffff0000, v184
	v_lshlrev_b32_e32 v122, 16, v184
	s_waitcnt vmcnt(28)
	v_and_b32_e32 v157, 0xffff0000, v187
	v_lshlrev_b32_e32 v156, 16, v187
	v_and_b32_e32 v125, 0xffff0000, v186
	v_lshlrev_b32_e32 v124, 16, v186
	v_pk_add_f32 v[110:111], v[110:111], v[126:127]
	v_pk_add_f32 v[108:109], v[108:109], v[118:119]
	v_pk_add_f32 v[106:107], v[106:107], v[152:153]
	v_pk_add_f32 v[104:105], v[104:105], v[120:121]
	v_pk_add_f32 v[102:103], v[102:103], v[154:155]
	v_pk_add_f32 v[100:101], v[100:101], v[122:123]
	v_pk_add_f32 v[118:119], v[96:97], v[124:125]
	v_cvt_pk_bf16_f32 v96, v108, v109
	v_cvt_pk_bf16_f32 v97, v110, v111
	v_mul_f32_e32 v109, v109, v109
	v_mul_f32_e32 v111, v111, v111
	v_cvt_pk_bf16_f32 v120, v104, v105
	v_mul_f32_e32 v105, v105, v105
	v_mul_f32_e32 v115, v107, v107
	v_pk_add_f32 v[98:99], v[98:99], v[156:157]
	v_mul_f32_e32 v121, v101, v101
	v_mul_f32_e32 v122, v103, v103
	v_fmac_f32_e32 v109, v108, v108
	v_fmac_f32_e32 v111, v110, v110
	v_fmac_f32_e32 v105, v104, v104
	v_fmac_f32_e32 v115, v106, v106
	v_mul_f32_e32 v123, v119, v119
	v_mul_f32_e32 v124, v99, v99
	global_store_dwordx2 v[116:117], v[96:97], off
	v_fmac_f32_e32 v121, v100, v100
	v_fmac_f32_e32 v122, v102, v102
	v_add_f32_e32 v96, v109, v111
	v_add_f32_e32 v97, v105, v115
	v_fmac_f32_e32 v123, v118, v118
	v_fmac_f32_e32 v124, v98, v98
	v_add_f32_e32 v104, v121, v122
	v_add_f32_e32 v96, v96, v97
	v_add_f32_e32 v96, v96, v104
	v_add_f32_e32 v97, v123, v124
	v_add_f32_e32 v96, v96, v97
	ds_bpermute_b32 v97, v151, v96
	v_cvt_pk_bf16_f32 v100, v100, v101
	v_cvt_pk_bf16_f32 v101, v102, v103
	v_cvt_pk_bf16_f32 v121, v106, v107
	global_store_dwordx2 v[116:117], v[100:101], off offset:256
	s_waitcnt lgkmcnt(0)
	v_add_f32_e32 v96, v96, v97
	ds_bpermute_b32 v97, v114, v96
	v_cvt_pk_bf16_f32 v100, v118, v119
	v_cvt_pk_bf16_f32 v101, v98, v99
	global_store_dwordx2 v[116:117], v[120:121], off offset:32
	global_store_dwordx2 v[116:117], v[100:101], off offset:288
	s_and_saveexec_b64 s[38:39], s[2:3]
	s_cbranch_execz .LBB0_1821
	v_lshl_add_u64 v[98:99], v[112:113], 2, s[12:13]
	s_waitcnt lgkmcnt(0)
	v_add_f32_e32 v96, v96, v97
	global_atomic_add_f32 v[98:99], v96, off
.LBB0_1821:
	s_or_b64 exec, exec, s[38:39]
	v_or_b32_e32 v96, 32, v142
	s_waitcnt lgkmcnt(0)
	v_ashrrev_i32_e32 v97, 31, v96
	v_lshlrev_b64 v[98:99], 10, v[96:97]
	v_lshl_add_u64 v[98:99], v[98:99], 0, v[140:141]
	v_lshl_add_u64 v[98:99], v[98:99], 1, s[26:27]
	s_waitcnt vmcnt(31)
	v_and_b32_e32 v109, 0xffff0000, v189
	v_lshlrev_b32_e32 v108, 16, v189
	v_and_b32_e32 v101, 0xffff0000, v188
	v_lshlrev_b32_e32 v100, 16, v188
	s_waitcnt vmcnt(30)
	v_and_b32_e32 v111, 0xffff0000, v191
	v_lshlrev_b32_e32 v110, 16, v191
	v_and_b32_e32 v103, 0xffff0000, v190
	v_lshlrev_b32_e32 v102, 16, v190
	s_waitcnt vmcnt(29)
	v_and_b32_e32 v113, 0xffff0000, v193
	v_lshlrev_b32_e32 v112, 16, v193
	v_and_b32_e32 v105, 0xffff0000, v192
	v_lshlrev_b32_e32 v104, 16, v192
	s_waitcnt vmcnt(28)
	v_and_b32_e32 v117, 0xffff0000, v195
	v_lshlrev_b32_e32 v116, 16, v195
	v_and_b32_e32 v107, 0xffff0000, v194
	v_lshlrev_b32_e32 v106, 16, v194
	v_pk_add_f32 v[94:95], v[94:95], v[108:109]
	v_pk_add_f32 v[92:93], v[92:93], v[100:101]
	v_pk_add_f32 v[90:91], v[90:91], v[110:111]
	v_pk_add_f32 v[88:89], v[88:89], v[102:103]
	v_pk_add_f32 v[86:87], v[86:87], v[112:113]
	v_pk_add_f32 v[84:85], v[84:85], v[104:105]
	v_pk_add_f32 v[100:101], v[80:81], v[106:107]
	v_cvt_pk_bf16_f32 v80, v92, v93
	v_cvt_pk_bf16_f32 v81, v94, v95
	v_mul_f32_e32 v93, v93, v93
	v_mul_f32_e32 v95, v95, v95
	v_cvt_pk_bf16_f32 v102, v88, v89
	v_mul_f32_e32 v89, v89, v89
	v_mul_f32_e32 v103, v91, v91
	v_pk_add_f32 v[82:83], v[82:83], v[116:117]
	v_mul_f32_e32 v104, v85, v85
	v_mul_f32_e32 v105, v87, v87
	v_fmac_f32_e32 v93, v92, v92
	v_fmac_f32_e32 v95, v94, v94
	v_fmac_f32_e32 v89, v88, v88
	v_fmac_f32_e32 v103, v90, v90
	v_mul_f32_e32 v106, v101, v101
	v_mul_f32_e32 v107, v83, v83
	global_store_dwordx2 v[98:99], v[80:81], off
	v_fmac_f32_e32 v104, v84, v84
	v_fmac_f32_e32 v105, v86, v86
	v_add_f32_e32 v80, v93, v95
	v_add_f32_e32 v81, v89, v103
	v_fmac_f32_e32 v106, v100, v100
	v_fmac_f32_e32 v107, v82, v82
	v_add_f32_e32 v88, v104, v105
	v_add_f32_e32 v80, v80, v81
	v_add_f32_e32 v80, v80, v88
	v_add_f32_e32 v81, v106, v107
	v_add_f32_e32 v80, v80, v81
	ds_bpermute_b32 v81, v151, v80
	v_cvt_pk_bf16_f32 v84, v84, v85
	v_cvt_pk_bf16_f32 v85, v86, v87
	v_cvt_pk_bf16_f32 v103, v90, v91
	global_store_dwordx2 v[98:99], v[84:85], off offset:256
	s_waitcnt lgkmcnt(0)
	v_add_f32_e32 v80, v80, v81
	ds_bpermute_b32 v81, v114, v80
	v_cvt_pk_bf16_f32 v84, v100, v101
	v_cvt_pk_bf16_f32 v85, v82, v83
	global_store_dwordx2 v[98:99], v[102:103], off offset:32
	global_store_dwordx2 v[98:99], v[84:85], off offset:288
	s_and_saveexec_b64 s[38:39], s[2:3]
	s_cbranch_execz .LBB0_1823
	v_lshl_add_u64 v[82:83], v[96:97], 2, s[12:13]
	s_waitcnt lgkmcnt(0)
	v_add_f32_e32 v80, v80, v81
	global_atomic_add_f32 v[82:83], v80, off
.LBB0_1823:
	s_or_b64 exec, exec, s[38:39]
	v_or_b32_e32 v80, 48, v142
	s_waitcnt lgkmcnt(0)
	v_ashrrev_i32_e32 v81, 31, v80
	v_lshlrev_b64 v[82:83], 10, v[80:81]
	v_lshl_add_u64 v[82:83], v[82:83], 0, v[140:141]
	v_lshl_add_u64 v[82:83], v[82:83], 1, s[26:27]
	s_waitcnt vmcnt(31)
	v_and_b32_e32 v93, 0xffff0000, v197
	v_lshlrev_b32_e32 v92, 16, v197
	v_and_b32_e32 v85, 0xffff0000, v196
	v_lshlrev_b32_e32 v84, 16, v196
	s_waitcnt vmcnt(30)
	v_and_b32_e32 v95, 0xffff0000, v199
	v_lshlrev_b32_e32 v94, 16, v199
	v_and_b32_e32 v87, 0xffff0000, v198
	v_lshlrev_b32_e32 v86, 16, v198
	s_waitcnt vmcnt(29)
	v_and_b32_e32 v97, 0xffff0000, v201
	v_lshlrev_b32_e32 v96, 16, v201
	v_and_b32_e32 v89, 0xffff0000, v200
	v_lshlrev_b32_e32 v88, 16, v200
	s_waitcnt vmcnt(28)
	v_and_b32_e32 v99, 0xffff0000, v203
	v_lshlrev_b32_e32 v98, 16, v203
	v_and_b32_e32 v91, 0xffff0000, v202
	v_lshlrev_b32_e32 v90, 16, v202
	v_pk_add_f32 v[78:79], v[78:79], v[92:93]
	v_pk_add_f32 v[76:77], v[76:77], v[84:85]
	v_pk_add_f32 v[74:75], v[74:75], v[94:95]
	v_pk_add_f32 v[72:73], v[72:73], v[86:87]
	v_pk_add_f32 v[70:71], v[70:71], v[96:97]
	v_pk_add_f32 v[68:69], v[68:69], v[88:89]
	v_pk_add_f32 v[84:85], v[64:65], v[90:91]
	v_cvt_pk_bf16_f32 v64, v76, v77
	v_cvt_pk_bf16_f32 v65, v78, v79
	v_mul_f32_e32 v77, v77, v77
	v_mul_f32_e32 v79, v79, v79
	v_cvt_pk_bf16_f32 v86, v72, v73
	v_mul_f32_e32 v73, v73, v73
	v_mul_f32_e32 v87, v75, v75
	v_pk_add_f32 v[66:67], v[66:67], v[98:99]
	v_mul_f32_e32 v88, v69, v69
	v_mul_f32_e32 v89, v71, v71
	v_fmac_f32_e32 v77, v76, v76
	v_fmac_f32_e32 v79, v78, v78
	v_fmac_f32_e32 v73, v72, v72
	v_fmac_f32_e32 v87, v74, v74
	v_mul_f32_e32 v90, v85, v85
	v_mul_f32_e32 v91, v67, v67
	global_store_dwordx2 v[82:83], v[64:65], off
	v_fmac_f32_e32 v88, v68, v68
	v_fmac_f32_e32 v89, v70, v70
	v_add_f32_e32 v64, v77, v79
	v_add_f32_e32 v65, v73, v87
	v_fmac_f32_e32 v90, v84, v84
	v_fmac_f32_e32 v91, v66, v66
	v_add_f32_e32 v72, v88, v89
	v_add_f32_e32 v64, v64, v65
	v_add_f32_e32 v64, v64, v72
	v_add_f32_e32 v65, v90, v91
	v_add_f32_e32 v64, v64, v65
	ds_bpermute_b32 v65, v151, v64
	v_cvt_pk_bf16_f32 v68, v68, v69
	v_cvt_pk_bf16_f32 v69, v70, v71
	v_cvt_pk_bf16_f32 v87, v74, v75
	global_store_dwordx2 v[82:83], v[68:69], off offset:256
	s_waitcnt lgkmcnt(0)
	v_add_f32_e32 v64, v64, v65
	ds_bpermute_b32 v65, v114, v64
	v_cvt_pk_bf16_f32 v68, v84, v85
	v_cvt_pk_bf16_f32 v69, v66, v67
	global_store_dwordx2 v[82:83], v[86:87], off offset:32
	global_store_dwordx2 v[82:83], v[68:69], off offset:288
	s_and_saveexec_b64 s[38:39], s[2:3]
	s_cbranch_execz .LBB0_1825
	v_lshl_add_u64 v[66:67], v[80:81], 2, s[12:13]
	s_waitcnt lgkmcnt(0)
	v_add_f32_e32 v64, v64, v65
	global_atomic_add_f32 v[66:67], v64, off
.LBB0_1825:
	s_or_b64 exec, exec, s[38:39]
	v_add_u32_e32 v64, 0x80, v142
	s_waitcnt lgkmcnt(0)
	v_ashrrev_i32_e32 v65, 31, v64
	v_lshlrev_b64 v[66:67], 10, v[64:65]
	v_lshl_add_u64 v[66:67], v[66:67], 0, v[140:141]
	v_lshl_add_u64 v[66:67], v[66:67], 1, s[26:27]
	s_waitcnt vmcnt(31)
	v_and_b32_e32 v77, 0xffff0000, v205
	v_lshlrev_b32_e32 v76, 16, v205
	v_and_b32_e32 v69, 0xffff0000, v204
	v_lshlrev_b32_e32 v68, 16, v204
	s_waitcnt vmcnt(30)
	v_and_b32_e32 v79, 0xffff0000, v207
	v_lshlrev_b32_e32 v78, 16, v207
	v_and_b32_e32 v71, 0xffff0000, v206
	v_lshlrev_b32_e32 v70, 16, v206
	s_waitcnt vmcnt(29)
	v_and_b32_e32 v81, 0xffff0000, v209
	v_lshlrev_b32_e32 v80, 16, v209
	v_and_b32_e32 v73, 0xffff0000, v208
	v_lshlrev_b32_e32 v72, 16, v208
	s_waitcnt vmcnt(28)
	v_and_b32_e32 v83, 0xffff0000, v211
	v_lshlrev_b32_e32 v82, 16, v211
	v_and_b32_e32 v75, 0xffff0000, v210
	v_lshlrev_b32_e32 v74, 16, v210
	v_pk_add_f32 v[62:63], v[62:63], v[76:77]
	v_pk_add_f32 v[60:61], v[60:61], v[68:69]
	v_pk_add_f32 v[58:59], v[58:59], v[78:79]
	v_pk_add_f32 v[56:57], v[56:57], v[70:71]
	v_pk_add_f32 v[54:55], v[54:55], v[80:81]
	v_pk_add_f32 v[52:53], v[52:53], v[72:73]
	v_pk_add_f32 v[68:69], v[48:49], v[74:75]
	v_cvt_pk_bf16_f32 v48, v60, v61
	v_cvt_pk_bf16_f32 v49, v62, v63
	v_mul_f32_e32 v61, v61, v61
	v_mul_f32_e32 v63, v63, v63
	v_cvt_pk_bf16_f32 v70, v56, v57
	v_mul_f32_e32 v57, v57, v57
	v_mul_f32_e32 v71, v59, v59
	v_pk_add_f32 v[50:51], v[50:51], v[82:83]
	v_mul_f32_e32 v72, v53, v53
	v_mul_f32_e32 v73, v55, v55
	v_fmac_f32_e32 v61, v60, v60
	v_fmac_f32_e32 v63, v62, v62
	v_fmac_f32_e32 v57, v56, v56
	v_fmac_f32_e32 v71, v58, v58
	v_mul_f32_e32 v74, v69, v69
	v_mul_f32_e32 v75, v51, v51
	global_store_dwordx2 v[66:67], v[48:49], off
	v_fmac_f32_e32 v72, v52, v52
	v_fmac_f32_e32 v73, v54, v54
	v_add_f32_e32 v48, v61, v63
	v_add_f32_e32 v49, v57, v71
	v_fmac_f32_e32 v74, v68, v68
	v_fmac_f32_e32 v75, v50, v50
	v_add_f32_e32 v56, v72, v73
	v_add_f32_e32 v48, v48, v49
	v_add_f32_e32 v48, v48, v56
	v_add_f32_e32 v49, v74, v75
	v_add_f32_e32 v48, v48, v49
	ds_bpermute_b32 v49, v151, v48
	v_cvt_pk_bf16_f32 v52, v52, v53
	v_cvt_pk_bf16_f32 v53, v54, v55
	v_cvt_pk_bf16_f32 v71, v58, v59
	global_store_dwordx2 v[66:67], v[52:53], off offset:256
	s_waitcnt lgkmcnt(0)
	v_add_f32_e32 v48, v48, v49
	ds_bpermute_b32 v49, v114, v48
	v_cvt_pk_bf16_f32 v52, v68, v69
	v_cvt_pk_bf16_f32 v53, v50, v51
	global_store_dwordx2 v[66:67], v[70:71], off offset:32
	global_store_dwordx2 v[66:67], v[52:53], off offset:288
	s_and_saveexec_b64 s[38:39], s[2:3]
	s_cbranch_execz .LBB0_1827
	v_lshl_add_u64 v[50:51], v[64:65], 2, s[12:13]
	s_waitcnt lgkmcnt(0)
	v_add_f32_e32 v48, v48, v49
	global_atomic_add_f32 v[50:51], v48, off
.LBB0_1827:
	s_or_b64 exec, exec, s[38:39]
	v_add_u32_e32 v48, 0x90, v142
	s_waitcnt lgkmcnt(0)
	v_ashrrev_i32_e32 v49, 31, v48
	v_lshlrev_b64 v[50:51], 10, v[48:49]
	v_lshl_add_u64 v[50:51], v[50:51], 0, v[140:141]
	v_lshl_add_u64 v[50:51], v[50:51], 1, s[26:27]
	s_waitcnt vmcnt(31)
	v_and_b32_e32 v61, 0xffff0000, v213
	v_lshlrev_b32_e32 v60, 16, v213
	v_and_b32_e32 v53, 0xffff0000, v212
	v_lshlrev_b32_e32 v52, 16, v212
	s_waitcnt vmcnt(30)
	v_and_b32_e32 v63, 0xffff0000, v215
	v_lshlrev_b32_e32 v62, 16, v215
	v_and_b32_e32 v55, 0xffff0000, v214
	v_lshlrev_b32_e32 v54, 16, v214
	s_waitcnt vmcnt(29)
	v_and_b32_e32 v65, 0xffff0000, v223
	v_lshlrev_b32_e32 v64, 16, v223
	v_and_b32_e32 v57, 0xffff0000, v222
	v_lshlrev_b32_e32 v56, 16, v222
	s_waitcnt vmcnt(28)
	v_and_b32_e32 v67, 0xffff0000, v225
	v_lshlrev_b32_e32 v66, 16, v225
	v_and_b32_e32 v59, 0xffff0000, v224
	v_lshlrev_b32_e32 v58, 16, v224
	v_pk_add_f32 v[46:47], v[46:47], v[60:61]
	v_pk_add_f32 v[44:45], v[44:45], v[52:53]
	v_pk_add_f32 v[42:43], v[42:43], v[62:63]
	v_pk_add_f32 v[40:41], v[40:41], v[54:55]
	v_pk_add_f32 v[38:39], v[38:39], v[64:65]
	v_pk_add_f32 v[36:37], v[36:37], v[56:57]
	v_pk_add_f32 v[52:53], v[32:33], v[58:59]
	v_cvt_pk_bf16_f32 v32, v44, v45
	v_cvt_pk_bf16_f32 v33, v46, v47
	v_mul_f32_e32 v45, v45, v45
	v_mul_f32_e32 v47, v47, v47
	v_cvt_pk_bf16_f32 v54, v40, v41
	v_mul_f32_e32 v41, v41, v41
	v_mul_f32_e32 v55, v43, v43
	v_pk_add_f32 v[34:35], v[34:35], v[66:67]
	v_mul_f32_e32 v56, v37, v37
	v_mul_f32_e32 v57, v39, v39
	v_fmac_f32_e32 v45, v44, v44
	v_fmac_f32_e32 v47, v46, v46
	v_fmac_f32_e32 v41, v40, v40
	v_fmac_f32_e32 v55, v42, v42
	v_mul_f32_e32 v58, v53, v53
	v_mul_f32_e32 v59, v35, v35
	global_store_dwordx2 v[50:51], v[32:33], off
	v_fmac_f32_e32 v56, v36, v36
	v_fmac_f32_e32 v57, v38, v38
	v_add_f32_e32 v32, v45, v47
	v_add_f32_e32 v33, v41, v55
	v_fmac_f32_e32 v58, v52, v52
	v_fmac_f32_e32 v59, v34, v34
	v_add_f32_e32 v40, v56, v57
	v_add_f32_e32 v32, v32, v33
	v_add_f32_e32 v32, v32, v40
	v_add_f32_e32 v33, v58, v59
	v_add_f32_e32 v32, v32, v33
	ds_bpermute_b32 v33, v151, v32
	v_cvt_pk_bf16_f32 v36, v36, v37
	v_cvt_pk_bf16_f32 v37, v38, v39
	v_cvt_pk_bf16_f32 v55, v42, v43
	global_store_dwordx2 v[50:51], v[36:37], off offset:256
	s_waitcnt lgkmcnt(0)
	v_add_f32_e32 v32, v32, v33
	ds_bpermute_b32 v33, v114, v32
	v_cvt_pk_bf16_f32 v36, v52, v53
	v_cvt_pk_bf16_f32 v37, v34, v35
	global_store_dwordx2 v[50:51], v[54:55], off offset:32
	global_store_dwordx2 v[50:51], v[36:37], off offset:288
	s_and_saveexec_b64 s[38:39], s[2:3]
	s_cbranch_execz .LBB0_1829
	v_lshl_add_u64 v[34:35], v[48:49], 2, s[12:13]
	s_waitcnt lgkmcnt(0)
	v_add_f32_e32 v32, v32, v33
	global_atomic_add_f32 v[34:35], v32, off
.LBB0_1829:
	s_or_b64 exec, exec, s[38:39]
	v_add_u32_e32 v32, 0xa0, v142
	s_waitcnt lgkmcnt(0)
	v_ashrrev_i32_e32 v33, 31, v32
	v_lshlrev_b64 v[34:35], 10, v[32:33]
	v_lshl_add_u64 v[34:35], v[34:35], 0, v[140:141]
	v_lshl_add_u64 v[34:35], v[34:35], 1, s[26:27]
	s_waitcnt vmcnt(31)
	v_and_b32_e32 v45, 0xffff0000, v227
	v_lshlrev_b32_e32 v44, 16, v227
	v_and_b32_e32 v37, 0xffff0000, v226
	v_lshlrev_b32_e32 v36, 16, v226
	s_waitcnt vmcnt(30)
	v_and_b32_e32 v47, 0xffff0000, v229
	v_lshlrev_b32_e32 v46, 16, v229
	v_and_b32_e32 v39, 0xffff0000, v228
	v_lshlrev_b32_e32 v38, 16, v228
	s_waitcnt vmcnt(29)
	v_and_b32_e32 v49, 0xffff0000, v231
	v_lshlrev_b32_e32 v48, 16, v231
	v_and_b32_e32 v41, 0xffff0000, v230
	v_lshlrev_b32_e32 v40, 16, v230
	s_waitcnt vmcnt(28)
	v_and_b32_e32 v51, 0xffff0000, v233
	v_lshlrev_b32_e32 v50, 16, v233
	v_and_b32_e32 v43, 0xffff0000, v232
	v_lshlrev_b32_e32 v42, 16, v232
	v_pk_add_f32 v[30:31], v[30:31], v[44:45]
	v_pk_add_f32 v[28:29], v[28:29], v[36:37]
	v_pk_add_f32 v[26:27], v[26:27], v[46:47]
	v_pk_add_f32 v[24:25], v[24:25], v[38:39]
	v_pk_add_f32 v[22:23], v[22:23], v[48:49]
	v_pk_add_f32 v[20:21], v[20:21], v[40:41]
	v_pk_add_f32 v[36:37], v[16:17], v[42:43]
	v_cvt_pk_bf16_f32 v16, v28, v29
	v_cvt_pk_bf16_f32 v17, v30, v31
	v_mul_f32_e32 v29, v29, v29
	v_mul_f32_e32 v31, v31, v31
	v_cvt_pk_bf16_f32 v38, v24, v25
	v_mul_f32_e32 v25, v25, v25
	v_mul_f32_e32 v39, v27, v27
	v_pk_add_f32 v[18:19], v[18:19], v[50:51]
	v_mul_f32_e32 v40, v21, v21
	v_mul_f32_e32 v41, v23, v23
	v_fmac_f32_e32 v29, v28, v28
	v_fmac_f32_e32 v31, v30, v30
	v_fmac_f32_e32 v25, v24, v24
	v_fmac_f32_e32 v39, v26, v26
	v_mul_f32_e32 v42, v37, v37
	v_mul_f32_e32 v43, v19, v19
	global_store_dwordx2 v[34:35], v[16:17], off
	v_fmac_f32_e32 v40, v20, v20
	v_fmac_f32_e32 v41, v22, v22
	v_add_f32_e32 v16, v29, v31
	v_add_f32_e32 v17, v25, v39
	v_fmac_f32_e32 v42, v36, v36
	v_fmac_f32_e32 v43, v18, v18
	v_add_f32_e32 v24, v40, v41
	v_add_f32_e32 v16, v16, v17
	v_add_f32_e32 v16, v16, v24
	v_add_f32_e32 v17, v42, v43
	v_add_f32_e32 v16, v16, v17
	ds_bpermute_b32 v17, v151, v16
	v_cvt_pk_bf16_f32 v20, v20, v21
	v_cvt_pk_bf16_f32 v21, v22, v23
	v_cvt_pk_bf16_f32 v39, v26, v27
	global_store_dwordx2 v[34:35], v[20:21], off offset:256
	s_waitcnt lgkmcnt(0)
	v_add_f32_e32 v16, v16, v17
	ds_bpermute_b32 v17, v114, v16
	v_cvt_pk_bf16_f32 v20, v36, v37
	v_cvt_pk_bf16_f32 v21, v18, v19
	global_store_dwordx2 v[34:35], v[38:39], off offset:32
	global_store_dwordx2 v[34:35], v[20:21], off offset:288
	s_and_saveexec_b64 s[38:39], s[2:3]
	s_cbranch_execz .LBB0_1831
	v_lshl_add_u64 v[18:19], v[32:33], 2, s[12:13]
	s_waitcnt lgkmcnt(0)
	v_add_f32_e32 v16, v16, v17
	global_atomic_add_f32 v[18:19], v16, off
.LBB0_1831:
	s_or_b64 exec, exec, s[38:39]
	v_add_u32_e32 v16, 0xb0, v142
	s_waitcnt lgkmcnt(0)
	v_ashrrev_i32_e32 v17, 31, v16
	v_lshlrev_b64 v[18:19], 10, v[16:17]
	v_lshl_add_u64 v[18:19], v[18:19], 0, v[140:141]
	v_lshl_add_u64 v[18:19], v[18:19], 1, s[26:27]
	s_waitcnt vmcnt(31)
	v_and_b32_e32 v29, 0xffff0000, v235
	v_lshlrev_b32_e32 v28, 16, v235
	v_and_b32_e32 v21, 0xffff0000, v234
	v_lshlrev_b32_e32 v20, 16, v234
	s_waitcnt vmcnt(30)
	v_and_b32_e32 v31, 0xffff0000, v237
	v_lshlrev_b32_e32 v30, 16, v237
	v_and_b32_e32 v23, 0xffff0000, v236
	v_lshlrev_b32_e32 v22, 16, v236
	s_waitcnt vmcnt(29)
	v_and_b32_e32 v33, 0xffff0000, v239
	v_lshlrev_b32_e32 v32, 16, v239
	v_and_b32_e32 v25, 0xffff0000, v238
	v_lshlrev_b32_e32 v24, 16, v238
	s_waitcnt vmcnt(28)
	v_and_b32_e32 v35, 0xffff0000, v241
	v_lshlrev_b32_e32 v34, 16, v241
	v_and_b32_e32 v27, 0xffff0000, v240
	v_lshlrev_b32_e32 v26, 16, v240
	v_pk_add_f32 v[14:15], v[14:15], v[28:29]
	v_pk_add_f32 v[12:13], v[12:13], v[20:21]
	v_pk_add_f32 v[10:11], v[10:11], v[30:31]
	v_pk_add_f32 v[8:9], v[8:9], v[22:23]
	v_pk_add_f32 v[6:7], v[6:7], v[32:33]
	v_pk_add_f32 v[4:5], v[4:5], v[24:25]
	v_pk_add_f32 v[20:21], v[0:1], v[26:27]
	v_cvt_pk_bf16_f32 v0, v12, v13
	v_cvt_pk_bf16_f32 v1, v14, v15
	v_mul_f32_e32 v13, v13, v13
	v_mul_f32_e32 v15, v15, v15
	v_cvt_pk_bf16_f32 v22, v8, v9
	v_mul_f32_e32 v9, v9, v9
	v_mul_f32_e32 v23, v11, v11
	v_pk_add_f32 v[2:3], v[2:3], v[34:35]
	v_mul_f32_e32 v24, v5, v5
	v_mul_f32_e32 v25, v7, v7
	v_fmac_f32_e32 v13, v12, v12
	v_fmac_f32_e32 v15, v14, v14
	v_fmac_f32_e32 v9, v8, v8
	v_fmac_f32_e32 v23, v10, v10
	v_mul_f32_e32 v26, v21, v21
	v_mul_f32_e32 v27, v3, v3
	global_store_dwordx2 v[18:19], v[0:1], off
	v_fmac_f32_e32 v24, v4, v4
	v_fmac_f32_e32 v25, v6, v6
	v_add_f32_e32 v0, v13, v15
	v_add_f32_e32 v1, v9, v23
	v_fmac_f32_e32 v26, v20, v20
	v_fmac_f32_e32 v27, v2, v2
	v_add_f32_e32 v8, v24, v25
	v_add_f32_e32 v0, v0, v1
	v_add_f32_e32 v0, v0, v8
	v_add_f32_e32 v1, v26, v27
	v_add_f32_e32 v0, v0, v1
	ds_bpermute_b32 v1, v151, v0
	v_cvt_pk_bf16_f32 v4, v4, v5
	v_cvt_pk_bf16_f32 v5, v6, v7
	v_cvt_pk_bf16_f32 v23, v10, v11
	global_store_dwordx2 v[18:19], v[4:5], off offset:256
	s_waitcnt lgkmcnt(0)
	v_add_f32_e32 v0, v0, v1
	ds_bpermute_b32 v1, v114, v0
	v_cvt_pk_bf16_f32 v4, v20, v21
	v_cvt_pk_bf16_f32 v5, v2, v3
	global_store_dwordx2 v[18:19], v[22:23], off offset:32
	global_store_dwordx2 v[18:19], v[4:5], off offset:288
	s_and_saveexec_b64 s[38:39], s[2:3]
	s_cbranch_execz .LBB0_1833
	v_lshl_add_u64 v[2:3], v[16:17], 2, s[12:13]
	s_waitcnt lgkmcnt(0)
	v_add_f32_e32 v0, v0, v1
	global_atomic_add_f32 v[2:3], v0, off
